# GDN chunk loop: next-chunk load addresses, o store address and o table offset kept in persistent VGPRs and bumped per chunk
# speedup vs baseline: 1.0111x; 1.0001x over previous
; #define LAS __attribute__((address_space(3)))
;     ...
;         constexpr int BUF = C::OFF_O + 2048;
;         rec_load<MIX, false>(R, proj, 0, sg, head, vcol0);
;         rec_process<MIX, false>(R, par, l, L, 0, sg, head);
;         __syncthreads();
;         rec_load<MIX, false>(R, proj, 1, sg, head, vcol0);
; #pragma unroll 1
;         for (int c = 0; c < SEQ / 64; ++c) {
;             LAS float* Lc = L + (c & 1) * BUF;
; #pragma unroll 1
;             for (int g = 0; g < (act ? 4 : 0); ++g) { float pp[16];
;                 gdn_group8(S, pp, 0, Lc, g * 16, kg, vl); gdn_group8(S, pp, 8, Lc, g * 16 + 8, kg, vl);
;                 Lc[C::OFF_O + (g * 16 + kg) * 32 + vl] = reduce_scatter16(pp, kg); }
;             if (c + 1 < SEQ / 64) { rec_process<MIX, false>(R, par, l, L + ((c + 1) & 1) * BUF, c + 1, sg, head);
;                 if (c + 2 < SEQ / 64) rec_load<MIX, false>(R, proj, c + 2, sg, head, vcol0);
;                 else if (DO_SAMPLE) rec_load<MIX, true>(R, proj, 0, sg, head, vcol0); }
;             __syncthreads();
;             rec_store_o<MIX, false>(Lc, raw, c, sg, MIX, head, vcol0, nv);
.LBB0_410:
	s_or_b64 exec, exec, s[4:5]
	v_mov_b32_e32 v0, v202
	s_waitcnt lgkmcnt(0)
	s_barrier
	s_lshl_b32 s2, s30, 6
	v_ashrrev_i32_e32 v1, 3, v0
	v_and_b32_e32 v2, 7, v0
	v_add3_u32 v3, v1, s10, 64
	v_mov_b64_e32 v[0:1], s[54:55]
	s_lshl_b32 s11, s34, 5
	v_mad_i64_i32 v[12:13], s[4:5], v3, s18, v[0:1]
	s_lshl_b32 s78, s2, 1
	s_mov_b32 s57, s79
	v_lshl_add_u64 v[8:9], v[12:13], 0, s[78:79]
	v_lshlrev_b32_e32 v0, 4, v2
	v_mov_b32_e32 v1, v17
	s_lshl_b32 s4, s11, 1
	s_mov_b32 s5, s79
	v_lshl_add_u64 v[12:13], v[12:13], 0, s[56:57]
	v_lshlrev_b32_e32 v16, 3, v2
	s_waitcnt vmcnt(0)
	v_lshl_add_u64 v[4:5], v[8:9], 0, v[0:1]
	v_lshl_add_u64 v[8:9], v[8:9], 0, s[4:5]
	v_add_co_u32_e32 v12, vcc, s20, v12
	v_lshl_add_u64 v[8:9], v[8:9], 0, v[16:17]
	s_nop 0
	v_addc_co_u32_e32 v13, vcc, 0, v13, vcc
	v_add_co_u32_e32 v176, vcc, 0x88000, v4
	s_nop 1
	v_addc_co_u32_e32 v177, vcc, 0, v5, vcc
	v_add_co_u32_e32 v178, vcc, 0x88000, v8
	s_nop 1
	v_addc_co_u32_e32 v179, vcc, 0, v9, vcc
	v_add_co_u32_e32 v180, vcc, 0x88000, v12
	s_nop 1
	v_addc_co_u32_e32 v181, vcc, 0, v13, vcc
	global_load_dwordx4 v[0:3], v[4:5], off offset:2048
	s_nop 0
	global_load_dwordx4 v[4:7], v[4:5], off offset:2560
	v_bfe_u32 v21, v10, 4, 2
	global_load_dwordx2 v[8:9], v[8:9], off offset:3072
	v_ashrrev_i32_e32 v11, 4, v10
	global_load_ushort v14, v[12:13], off
	v_and_b32_e32 v20, 15, v10
	global_load_ushort v12, v[12:13], off offset:8
	v_and_b32_e32 v13, 2, v10
	v_and_b32_e32 v22, -4, v11
	s_add_i32 s2, 0, 0x8000
	v_cmp_gt_i32_e64 s[42:43], 32, v22
	s_mov_b32 s12, 0
	v_cmp_gt_u32_e64 s[44:45], 8, v20
	v_cmp_eq_u32_e64 s[48:49], 0, v13
	s_or_b32 s13, s10, 0x80
	v_lshl_add_u32 v26, v20, 4, 0
	s_waitcnt vmcnt(1)
	v_mov_b32_e32 v23, v14
	s_waitcnt vmcnt(0)
	v_mov_b32_e32 v24, v12
	v_and_b32_e32 v12, 4, v10
	v_and_b32_e32 v10, 1, v10
	v_cmp_eq_u32_e64 s[50:51], 0, v10
	v_lshlrev_b32_e32 v10, 2, v11
	v_lshlrev_b32_e32 v11, 2, v21
	v_and_or_b32 v10, v10, -16, v11
	v_add_u32_e32 v25, s2, v10
	v_lshlrev_b32_e32 v11, 7, v20
	s_add_i32 s2, 0, 0xc400
	v_add3_u32 v27, v10, v11, s2
	v_mov_b32_e32 v10, 0
	v_cmp_eq_u32_e64 s[46:47], 0, v12
	v_mov_b32_e32 v11, v10
	v_mov_b32_e32 v12, v10
	v_mov_b32_e32 v13, v10
	v_ashrrev_i32_e32 v187, 3, v202
	v_lshlrev_b32_e32 v186, 2, v202
	v_and_b32_e32 v186, 28, v186
	v_lshlrev_b32_e32 v182, 7, v187
	v_lshl_add_u32 v182, v186, 2, v182
	v_add_u32_e32 v184, s10, v187
	v_ashrrev_i32_e32 v185, 31, v184
	v_lshlrev_b64 v[184:185], 11, v[184:185]
	v_lshl_add_u64 v[184:185], s[52:53], 0, v[184:185]
	v_lshl_add_u64 v[184:185], v[184:185], 0, s[78:79]
	v_lshl_add_u64 v[184:185], v[184:185], 0, s[4:5]
	v_lshlrev_b32_e32 v186, 1, v186
	v_mov_b32_e32 v187, 0
	v_lshl_add_u64 v[184:185], v[184:185], 0, v[186:187]
	v_add_co_u32_e32 v184, vcc, 0x3500000, v184
	s_nop 1
	v_addc_co_u32_e32 v185, vcc, 0, v185, vcc
	s_bitcmp1_b32 s12, 0
	s_cselect_b32 s22, 0x3900, 0
	s_and_saveexec_b64 s[6:7], s[42:43]
	s_cbranch_execz .LBB0_413

; #define LAS __attribute__((address_space(3)))
; __device__ __forceinline__ int tidx() { int t = threadIdx.x; asm volatile("" : "+v"(t)); return t; }
;     typedef RecCfg<MIX> C;
;     const int tid = tidx(), s = tid >> 3, c4 = (tid & 7) * 4;
;     const Slot sl = slot_of<SAMPLE>(chunk, s, sg);
;     f32x4 o = *(const LAS f32x4*)(L + C::OFF_O + s * 32 + c4);
;     if constexpr (MIX == 3) o = o + *(const LAS f32x4*)(L + C::OFF_XSD + s * 32 + c4);
;     u32x2 w; w.x = pkh(o[0], o[1]); w.y = pkh(o[2], o[3]);
;     if (c4 < nv) *(u32x2*)(raw + (size_t)sl.row * DM + mixer * 256 + head * 64 + vcol0 + c4) = w;
; }
;     ...
;             if (c + 1 < SEQ / 64) { rec_process<MIX, false>(R, par, l, L + ((c + 1) & 1) * BUF, c + 1, sg, head);
;                 if (c + 2 < SEQ / 64) rec_load<MIX, false>(R, proj, c + 2, sg, head, vcol0);
;                 else if (DO_SAMPLE) rec_load<MIX, true>(R, proj, 0, sg, head, vcol0); }
;             __syncthreads();
;             rec_store_o<MIX, false>(Lc, raw, c, sg, MIX, head, vcol0, nv);
.LBB0_418:
	s_or_b64 exec, exec, s[6:7]
	s_cmp_gt_u32 s12, 29
	s_cbranch_scc1 .LBB0_420
	global_load_dwordx2 v[8:9], v[178:179], off offset:3072
	global_load_ushort v23, v[180:181], off
	global_load_ushort v24, v[180:181], off offset:8
	global_load_dwordx4 v[0:3], v[176:177], off offset:2048
	global_load_dwordx4 v[4:7], v[176:177], off offset:2560
	v_add_co_u32_e32 v176, vcc, 0x88000, v176
	s_mov_b32 s5, s79
	s_nop 0
	v_addc_co_u32_e32 v177, vcc, 0, v177, vcc
	v_add_co_u32_e32 v178, vcc, 0x88000, v178
	s_nop 1
	v_addc_co_u32_e32 v179, vcc, 0, v179, vcc
	v_add_co_u32_e32 v180, vcc, 0x88000, v180
	s_nop 1
	v_addc_co_u32_e32 v181, vcc, 0, v181, vcc
.LBB0_420:
	s_waitcnt lgkmcnt(0)
	s_barrier
	s_lshl_b32 s3, s22, 2
	s_mov_b32 s5, s79
	v_add_u32_e32 v14, s3, v182
	ds_read_b128 v[28:31], v14 offset:50176
	s_waitcnt lgkmcnt(0)
	v_cvt_pk_f16_f32 v28, v28, v29
	v_cvt_pk_f16_f32 v29, v30, v31
	s_cmp_eq_u32 s2, 32
	global_store_dwordx2 v[184:185], v[28:29], off offset:512
	v_add_co_u32_e32 v184, vcc, 0x20000, v184
	s_nop 1
	v_addc_co_u32_e32 v185, vcc, 0, v185, vcc
	s_cbranch_scc1 .LBB0_422
	s_mov_b32 s12, s2
	s_bitcmp1_b32 s12, 0
	s_cselect_b32 s22, 0x3900, 0
	s_and_saveexec_b64 s[6:7], s[42:43]
	s_cbranch_execnz .LBB0_411
	s_branch .LBB0_413
